# attention tile loops: 27 v_pk_add_f32 per loop (subtract-max, row-sum tree) split into scalar v_add_f32 pairs
# speedup vs baseline: 1.0040x; 1.0009x over previous
; #define LAS __attribute__((address_space(3)))
; DI unsigned cvtpk(float lo, float hi) { f32x2_t v = {lo, hi}; bf16x2_t b = __builtin_convertvector(v, bf16x2_t); return __builtin_bit_cast(unsigned, b); }
; DI float fexp2(float x) { return __builtin_amdgcn_exp2f(x); }
; #define MFMA32(a, b, c) __builtin_amdgcn_mfma_f32_32x32x16_bf16((a), (b), (c), 0, 0, 0)
;     ...
;             const float mu = (m == -INFINITY) ? 0.f : m;
;             float rs = 0.f;
; #pragma unroll
;             for (int i = 0; i < 16; i += 2) {
;                 f32x2_t a2 = {s0[i], s0[i + 1]}, b2 = {s1[i], s1[i + 1]}; const f32x2_t nm = {-mu, -mu};
;                 a2 = a2 + nm; b2 = b2 + nm;
;                 s0[i] = fexp2(a2.x); s0[i + 1] = fexp2(a2.y); s1[i] = fexp2(b2.x); s1[i + 1] = fexp2(b2.y);
;                 rs += (s0[i] + s0[i + 1]) + (s1[i] + s1[i + 1]); }
;             l += rs;
;             bf16x8 pb[4];
;             { u32x4 p; p.x = cvtpk(s0[0], s0[1]); p.y = cvtpk(s0[2], s0[3]); p.z = cvtpk(s0[4], s0[5]); p.w = cvtpk(s0[6], s0[7]); pb[0] = __builtin_bit_cast(bf16x8, p);
;               p.x = cvtpk(s0[8], s0[9]); p.y = cvtpk(s0[10], s0[11]); p.z = cvtpk(s0[12], s0[13]); p.w = cvtpk(s0[14], s0[15]); pb[1] = __builtin_bit_cast(bf16x8, p);
;               p.x = cvtpk(s1[0], s1[1]); p.y = cvtpk(s1[2], s1[3]); p.z = cvtpk(s1[4], s1[5]); p.w = cvtpk(s1[6], s1[7]); pb[2] = __builtin_bit_cast(bf16x8, p);
;               p.x = cvtpk(s1[8], s1[9]); p.y = cvtpk(s1[10], s1[11]); p.z = cvtpk(s1[12], s1[13]); p.w = cvtpk(s1[14], s1[15]); pb[3] = __builtin_bit_cast(bf16x8, p); }
;             const LAS unsigned char* vb = bb + KB + n * PV + 8 * h;
; #pragma unroll
;             for (int sx = 0; sx < 4; ++sx) {
;                 const s16x4 a0 = *(const LAS s16x4*)(vb + 32 * sx), a1 = *(const LAS s16x4*)(vb + 32 * sx + 16);
;                 const s16x4 b0 = *(const LAS s16x4*)(vb + 32 * PV + 32 * sx), b1 = *(const LAS s16x4*)(vb + 32 * PV + 32 * sx + 16);
;                 o0 = MFMA32(__builtin_shufflevector(a0, a1, 0, 1, 2, 3, 4, 5, 6, 7), pb[sx], o0);
;                 o1 = MFMA32(__builtin_shufflevector(b0, b1, 0, 1, 2, 3, 4, 5, 6, 7), pb[sx], o1);
.LBB0_137:
	v_cmp_neq_f32_e32 vcc, s79, v127
	s_nop 1
	v_cndmask_b32_e64 v128, v247, -v127, vcc
	v_add_f32_e32 v66, v66, v128
	v_add_f32_e32 v67, v67, v128
	v_add_f32_e32 v82, v82, v128
	v_add_f32_e32 v83, v83, v128
	v_add_f32_e32 v68, v68, v128
	v_add_f32_e32 v69, v69, v128
	v_add_f32_e32 v84, v84, v128
	v_add_f32_e32 v85, v85, v128
	v_exp_f32_e32 v147, v66
	v_exp_f32_e32 v67, v67
	v_exp_f32_e32 v149, v82
	v_exp_f32_e32 v83, v83
	v_exp_f32_e32 v146, v68
	v_exp_f32_e32 v66, v69
	v_exp_f32_e32 v148, v84
	v_exp_f32_e32 v82, v85
	v_add_f32_e32 v70, v70, v128
	v_add_f32_e32 v71, v71, v128
	v_add_f32_e32 v68, v66, v146
	v_add_f32_e32 v69, v67, v147
	v_exp_f32_e32 v151, v71
	v_add_f32_e32 v84, v82, v148
	v_add_f32_e32 v85, v83, v149
	v_add_f32_e32 v72, v72, v128
	v_add_f32_e32 v73, v73, v128
	v_add_f32_e32 v68, v84, v68
	v_add_f32_e32 v69, v85, v69
	v_add_f32_e32 v84, v86, v128
	v_add_f32_e32 v85, v87, v128
	v_exp_f32_e32 v87, v70
	v_exp_f32_e32 v86, v84
	v_exp_f32_e32 v150, v85
	v_add_f32_e32 v84, v88, v128
	v_add_f32_e32 v85, v89, v128
	v_add_f32_e32 v69, 0, v69
	v_exp_f32_e32 v154, v72
	v_add_f32_e32 v70, v150, v86
	v_add_f32_e32 v71, v151, v87
	v_exp_f32_e32 v155, v73
	v_pk_add_f32 v[70:71], v[70:71], v[70:71] op_sel_hi:[0,1]
	v_exp_f32_e32 v156, v84
	v_exp_f32_e32 v157, v85
	v_add_f32_e32 v72, v74, v128
	v_add_f32_e32 v73, v75, v128
	v_add_f32_e32 v74, v90, v128
	v_add_f32_e32 v75, v91, v128
	v_add_f32_e32 v69, v68, v69
	v_exp_f32_e32 v68, v72
	v_exp_f32_e32 v70, v73
	v_exp_f32_e32 v84, v74
	v_exp_f32_e32 v88, v75
	v_add_f32_e32 v85, v155, v154
	v_add_f32_e32 v89, v157, v156
	v_add_f32_e32 v72, v70, v68
	v_add_f32_e32 v73, v71, v69
	v_add_f32_e32 v74, v88, v84
	v_add_f32_e32 v75, v89, v85
	s_nop 0
	v_add_f32_e32 v72, v74, v72
	v_add_f32_e32 v73, v75, v73
	v_add_f32_e32 v74, v76, v128
	v_add_f32_e32 v75, v77, v128
	v_add_f32_e32 v76, v92, v128
	v_add_f32_e32 v77, v93, v128
	v_exp_f32_e32 v91, v74
	v_exp_f32_e32 v93, v75
	v_exp_f32_e32 v90, v76
	v_exp_f32_e32 v92, v77
	v_add_f32_e32 v76, v94, v128
	v_add_f32_e32 v77, v95, v128
	v_pk_add_f32 v[72:73], v[72:73], v[72:73] op_sel_hi:[0,1]
	v_exp_f32_e32 v85, v76
	v_exp_f32_e32 v89, v77
	v_add_f32_e32 v74, v92, v90
	v_add_f32_e32 v75, v93, v91
	s_nop 0
	v_pk_add_f32 v[152:153], v[74:75], v[74:75] op_sel_hi:[0,1]
	v_add_f32_e32 v74, v78, v128
	v_add_f32_e32 v75, v79, v128
	v_add_f32_e32 v129, v89, v85
	v_exp_f32_e32 v69, v74
	v_exp_f32_e32 v71, v75
	v_add_f32_e32 v74, v80, v128
	v_add_f32_e32 v75, v81, v128
	v_add_f32_e32 v76, v96, v128
	v_add_f32_e32 v77, v97, v128
	v_exp_f32_e32 v72, v74
	v_exp_f32_e32 v152, v75
	v_exp_f32_e32 v94, v76
	v_exp_f32_e32 v128, v77
	v_add_f32_e32 v95, v71, v69
	v_add_f32_e32 v74, v152, v72
	v_add_f32_e32 v75, v153, v73
	v_cvt_pk_bf16_f32 v79, v146, v66
	v_add_f32_e32 v76, v128, v94
	v_add_f32_e32 v77, v129, v95
	v_cvt_pk_bf16_f32 v66, v84, v88
	v_add_f32_e32 v74, v76, v74
	v_add_f32_e32 v75, v77, v75
	v_cvt_pk_bf16_f32 v77, v72, v152
	v_cvt_pk_bf16_f32 v72, v86, v150
	v_add3_u32 v86, s38, v188, v164
	v_cvt_pk_bf16_f32 v76, v69, v71
	v_cvt_pk_bf16_f32 v69, v94, v128
	v_add_u32_e32 v94, 0x3000, v86
	v_add_f32_e32 v73, v74, v75
	v_cvt_pk_bf16_f32 v74, v68, v70
	v_cvt_pk_bf16_f32 v70, v149, v83
	v_cvt_pk_bf16_f32 v71, v148, v82
	v_cvt_pk_bf16_f32 v68, v85, v89
	ds_read2_b64 v[82:85], v94 offset0:160 offset1:162
	v_add_u32_e32 v95, 0x2000, v86
	v_cvt_pk_bf16_f32 v78, v147, v67
	v_cvt_pk_bf16_f32 v80, v87, v151
	v_cvt_pk_bf16_f32 v75, v91, v93
	v_cvt_pk_bf16_f32 v67, v90, v92
	ds_read2_b64 v[86:89], v95 offset0:128 offset1:130
	ds_read2_b64 v[90:93], v95 offset0:132 offset1:134
	v_cvt_pk_bf16_f32 v81, v154, v155
	v_add_f32_e32 v201, v201, v73
	v_cvt_pk_bf16_f32 v73, v156, v157
	s_waitcnt lgkmcnt(1)
	v_mfma_f32_32x32x16_bf16 v[34:49], v[86:89], v[78:81], v[34:49]
	v_mfma_f32_32x32x16_bf16 v[50:65], v[82:85], v[78:81], v[50:65]
	ds_read2_b64 v[78:81], v94 offset0:164 offset1:166
	s_waitcnt lgkmcnt(1)
	v_mfma_f32_32x32x16_bf16 v[34:49], v[90:93], v[74:77], v[34:49]
	s_waitcnt lgkmcnt(0)
	v_mfma_f32_32x32x16_bf16 v[50:65], v[78:81], v[74:77], v[50:65]
	ds_read2_b64 v[74:77], v95 offset0:136 offset1:138
	ds_read2_b64 v[78:81], v94 offset0:168 offset1:170
	s_waitcnt lgkmcnt(1)
	v_mfma_f32_32x32x16_bf16 v[34:49], v[74:77], v[70:73], v[34:49]
	s_waitcnt lgkmcnt(0)
	v_mfma_f32_32x32x16_bf16 v[50:65], v[78:81], v[70:73], v[50:65]
	ds_read2_b64 v[70:73], v95 offset0:140 offset1:142
	ds_read2_b64 v[74:77], v94 offset0:172 offset1:174
	s_waitcnt lgkmcnt(1)
	v_mfma_f32_32x32x16_bf16 v[34:49], v[70:73], v[66:69], v[34:49]
	s_waitcnt lgkmcnt(0)
	v_mfma_f32_32x32x16_bf16 v[50:65], v[74:77], v[66:69], v[50:65]

; #define LAS __attribute__((address_space(3)))
; DI unsigned cvtpk(float lo, float hi) { f32x2_t v = {lo, hi}; bf16x2_t b = __builtin_convertvector(v, bf16x2_t); return __builtin_bit_cast(unsigned, b); }
; DI float fexp2(float x) { return __builtin_amdgcn_exp2f(x); }
; #define MFMA32(a, b, c) __builtin_amdgcn_mfma_f32_32x32x16_bf16((a), (b), (c), 0, 0, 0)
;     ...
;             const float mu = (m == -INFINITY) ? 0.f : m;
;             float rs = 0.f;
; #pragma unroll
;             for (int i = 0; i < 16; i += 2) {
;                 f32x2_t a2 = {s0[i], s0[i + 1]}, b2 = {s1[i], s1[i + 1]}; const f32x2_t nm = {-mu, -mu};
;                 a2 = a2 + nm; b2 = b2 + nm;
;                 s0[i] = fexp2(a2.x); s0[i + 1] = fexp2(a2.y); s1[i] = fexp2(b2.x); s1[i + 1] = fexp2(b2.y);
;                 rs += (s0[i] + s0[i + 1]) + (s1[i] + s1[i + 1]); }
;             l += rs;
;             bf16x8 pb[4];
;             { u32x4 p; p.x = cvtpk(s0[0], s0[1]); p.y = cvtpk(s0[2], s0[3]); p.z = cvtpk(s0[4], s0[5]); p.w = cvtpk(s0[6], s0[7]); pb[0] = __builtin_bit_cast(bf16x8, p);
;               p.x = cvtpk(s0[8], s0[9]); p.y = cvtpk(s0[10], s0[11]); p.z = cvtpk(s0[12], s0[13]); p.w = cvtpk(s0[14], s0[15]); pb[1] = __builtin_bit_cast(bf16x8, p);
;               p.x = cvtpk(s1[0], s1[1]); p.y = cvtpk(s1[2], s1[3]); p.z = cvtpk(s1[4], s1[5]); p.w = cvtpk(s1[6], s1[7]); pb[2] = __builtin_bit_cast(bf16x8, p);
;               p.x = cvtpk(s1[8], s1[9]); p.y = cvtpk(s1[10], s1[11]); p.z = cvtpk(s1[12], s1[13]); p.w = cvtpk(s1[14], s1[15]); pb[3] = __builtin_bit_cast(bf16x8, p); }
;             const LAS unsigned char* vb = bb + KB + n * PV + 8 * h;
; #pragma unroll
;             for (int sx = 0; sx < 4; ++sx) {
;                 const s16x4 a0 = *(const LAS s16x4*)(vb + 32 * sx), a1 = *(const LAS s16x4*)(vb + 32 * sx + 16);
;                 const s16x4 b0 = *(const LAS s16x4*)(vb + 32 * PV + 32 * sx), b1 = *(const LAS s16x4*)(vb + 32 * PV + 32 * sx + 16);
;                 o0 = MFMA32(__builtin_shufflevector(a0, a1, 0, 1, 2, 3, 4, 5, 6, 7), pb[sx], o0);
;                 o1 = MFMA32(__builtin_shufflevector(b0, b1, 0, 1, 2, 3, 4, 5, 6, 7), pb[sx], o1);
;             }
.LBB0_155:
	v_cmp_neq_f32_e32 vcc, s79, v213
	s_nop 1
	v_cndmask_b32_e64 v202, v247, -v213, vcc
	v_add_f32_e32 v98, v98, v202
	v_add_f32_e32 v99, v99, v202
	v_add_f32_e32 v114, v114, v202
	v_add_f32_e32 v115, v115, v202
	v_add_f32_e32 v100, v100, v202
	v_add_f32_e32 v101, v101, v202
	v_add_f32_e32 v116, v116, v202
	v_add_f32_e32 v117, v117, v202
	v_exp_f32_e32 v205, v98
	v_exp_f32_e32 v99, v99
	v_exp_f32_e32 v215, v114
	v_exp_f32_e32 v115, v115
	v_exp_f32_e32 v204, v100
	v_exp_f32_e32 v98, v101
	v_exp_f32_e32 v214, v116
	v_exp_f32_e32 v114, v117
	v_add_f32_e32 v102, v102, v202
	v_add_f32_e32 v103, v103, v202
	v_add_f32_e32 v100, v98, v204
	v_add_f32_e32 v101, v99, v205
	v_exp_f32_e32 v217, v103
	v_add_f32_e32 v116, v114, v214
	v_add_f32_e32 v117, v115, v215
	v_add_f32_e32 v104, v104, v202
	v_add_f32_e32 v105, v105, v202
	v_add_f32_e32 v100, v116, v100
	v_add_f32_e32 v101, v117, v101
	v_add_f32_e32 v116, v118, v202
	v_add_f32_e32 v117, v119, v202
	v_exp_f32_e32 v119, v102
	v_exp_f32_e32 v118, v116
	v_exp_f32_e32 v216, v117
	v_add_f32_e32 v116, v120, v202
	v_add_f32_e32 v117, v121, v202
	v_add_f32_e32 v101, 0, v101
	v_exp_f32_e32 v220, v104
	v_add_f32_e32 v102, v216, v118
	v_add_f32_e32 v103, v217, v119
	v_exp_f32_e32 v221, v105
	v_pk_add_f32 v[102:103], v[102:103], v[102:103] op_sel_hi:[0,1]
	v_exp_f32_e32 v222, v116
	v_exp_f32_e32 v223, v117
	v_add_f32_e32 v104, v106, v202
	v_add_f32_e32 v105, v107, v202
	v_add_f32_e32 v106, v122, v202
	v_add_f32_e32 v107, v123, v202
	v_add_f32_e32 v101, v100, v101
	v_exp_f32_e32 v100, v104
	v_exp_f32_e32 v102, v105
	v_exp_f32_e32 v116, v106
	v_exp_f32_e32 v120, v107
	v_add_f32_e32 v117, v221, v220
	v_add_f32_e32 v121, v223, v222
	v_add_f32_e32 v104, v102, v100
	v_add_f32_e32 v105, v103, v101
	v_add_f32_e32 v106, v120, v116
	v_add_f32_e32 v107, v121, v117
	s_nop 0
	v_add_f32_e32 v104, v106, v104
	v_add_f32_e32 v105, v107, v105
	v_add_f32_e32 v106, v108, v202
	v_add_f32_e32 v107, v109, v202
	v_add_f32_e32 v108, v124, v202
	v_add_f32_e32 v109, v125, v202
	v_exp_f32_e32 v123, v106
	v_exp_f32_e32 v125, v107
	v_exp_f32_e32 v122, v108
	v_exp_f32_e32 v124, v109
	v_add_f32_e32 v108, v126, v202
	v_add_f32_e32 v109, v127, v202
	v_pk_add_f32 v[104:105], v[104:105], v[104:105] op_sel_hi:[0,1]
	v_exp_f32_e32 v117, v108
	v_exp_f32_e32 v121, v109
	v_add_f32_e32 v106, v124, v122
	v_add_f32_e32 v107, v125, v123
	s_nop 0
	v_pk_add_f32 v[218:219], v[106:107], v[106:107] op_sel_hi:[0,1]
	v_add_f32_e32 v106, v110, v202
	v_add_f32_e32 v107, v111, v202
	v_add_f32_e32 v203, v121, v117
	v_exp_f32_e32 v101, v106
	v_exp_f32_e32 v103, v107
	v_add_f32_e32 v106, v112, v202
	v_add_f32_e32 v107, v113, v202
	v_add_f32_e32 v108, v128, v202
	v_add_f32_e32 v109, v129, v202
	v_exp_f32_e32 v104, v106
	v_exp_f32_e32 v218, v107
	v_exp_f32_e32 v126, v108
	v_exp_f32_e32 v202, v109
	v_add_f32_e32 v127, v103, v101
	v_add_f32_e32 v106, v218, v104
	v_add_f32_e32 v107, v219, v105
	v_cvt_pk_bf16_f32 v111, v204, v98
	v_add_f32_e32 v108, v202, v126
	v_add_f32_e32 v109, v203, v127
	v_cvt_pk_bf16_f32 v98, v116, v120
	v_add_f32_e32 v106, v108, v106
	v_add_f32_e32 v107, v109, v107
	v_cvt_pk_bf16_f32 v109, v104, v218
	v_cvt_pk_bf16_f32 v104, v118, v216
	v_add3_u32 v118, s9, v188, v164
	v_cvt_pk_bf16_f32 v108, v101, v103
	v_cvt_pk_bf16_f32 v101, v126, v202
	v_add_u32_e32 v126, 0x3000, v118
	v_add_f32_e32 v105, v106, v107
	v_cvt_pk_bf16_f32 v106, v100, v102
	v_cvt_pk_bf16_f32 v102, v215, v115
	v_cvt_pk_bf16_f32 v103, v214, v114
	v_cvt_pk_bf16_f32 v100, v117, v121
	ds_read2_b64 v[114:117], v126 offset0:160 offset1:162
	v_add_u32_e32 v127, 0x2000, v118
	v_cvt_pk_bf16_f32 v110, v205, v99
	v_cvt_pk_bf16_f32 v112, v119, v217
	v_cvt_pk_bf16_f32 v107, v123, v125
	v_cvt_pk_bf16_f32 v99, v122, v124
	ds_read2_b64 v[118:121], v127 offset0:128 offset1:130
	ds_read2_b64 v[122:125], v127 offset0:132 offset1:134
	v_cvt_pk_bf16_f32 v113, v220, v221
	v_add_f32_e32 v211, v211, v105
	v_cvt_pk_bf16_f32 v105, v222, v223
	s_waitcnt lgkmcnt(1)
	v_mfma_f32_32x32x16_bf16 v[66:81], v[118:121], v[110:113], v[66:81]
	v_mfma_f32_32x32x16_bf16 v[82:97], v[114:117], v[110:113], v[82:97]
	ds_read2_b64 v[110:113], v126 offset0:164 offset1:166
	s_waitcnt lgkmcnt(1)
	v_mfma_f32_32x32x16_bf16 v[66:81], v[122:125], v[106:109], v[66:81]
	s_waitcnt lgkmcnt(0)
	v_mfma_f32_32x32x16_bf16 v[82:97], v[110:113], v[106:109], v[82:97]
	ds_read2_b64 v[106:109], v127 offset0:136 offset1:138
	ds_read2_b64 v[110:113], v126 offset0:168 offset1:170
	s_waitcnt lgkmcnt(1)
	v_mfma_f32_32x32x16_bf16 v[66:81], v[106:109], v[102:105], v[66:81]
	s_waitcnt lgkmcnt(0)
	v_mfma_f32_32x32x16_bf16 v[82:97], v[110:113], v[102:105], v[82:97]
	ds_read2_b64 v[102:105], v127 offset0:140 offset1:142
	ds_read2_b64 v[106:109], v126 offset0:172 offset1:174
	s_waitcnt lgkmcnt(1)
	v_mfma_f32_32x32x16_bf16 v[66:81], v[102:105], v[98:101], v[66:81]
	s_waitcnt lgkmcnt(0)
	v_mfma_f32_32x32x16_bf16 v[82:97], v[106:109], v[98:101], v[82:97]
	s_cmp_ge_i32 s24, s58
	s_mov_b64 s[10:11], -1
	s_cbranch_scc0 .LBB0_158

; #define LAS __attribute__((address_space(3)))
; DI unsigned cvtpk(float lo, float hi) { f32x2_t v = {lo, hi}; bf16x2_t b = __builtin_convertvector(v, bf16x2_t); return __builtin_bit_cast(unsigned, b); }
; DI float fexp2(float x) { return __builtin_amdgcn_exp2f(x); }
; #define MFMA32(a, b, c) __builtin_amdgcn_mfma_f32_32x32x16_bf16((a), (b), (c), 0, 0, 0)
;     ...
;             const float mu = (m == -INFINITY) ? 0.f : m;
;             float rs = 0.f;
; #pragma unroll
;             for (int i = 0; i < 16; i += 2) {
;                 f32x2_t a2 = {s0[i], s0[i + 1]}, b2 = {s1[i], s1[i + 1]}; const f32x2_t nm = {-mu, -mu};
;                 a2 = a2 + nm; b2 = b2 + nm;
;                 s0[i] = fexp2(a2.x); s0[i + 1] = fexp2(a2.y); s1[i] = fexp2(b2.x); s1[i + 1] = fexp2(b2.y);
;                 rs += (s0[i] + s0[i + 1]) + (s1[i] + s1[i + 1]); }
;             l += rs;
;             bf16x8 pb[4];
;             { u32x4 p; p.x = cvtpk(s0[0], s0[1]); p.y = cvtpk(s0[2], s0[3]); p.z = cvtpk(s0[4], s0[5]); p.w = cvtpk(s0[6], s0[7]); pb[0] = __builtin_bit_cast(bf16x8, p);
;               p.x = cvtpk(s0[8], s0[9]); p.y = cvtpk(s0[10], s0[11]); p.z = cvtpk(s0[12], s0[13]); p.w = cvtpk(s0[14], s0[15]); pb[1] = __builtin_bit_cast(bf16x8, p);
;               p.x = cvtpk(s1[0], s1[1]); p.y = cvtpk(s1[2], s1[3]); p.z = cvtpk(s1[4], s1[5]); p.w = cvtpk(s1[6], s1[7]); pb[2] = __builtin_bit_cast(bf16x8, p);
;               p.x = cvtpk(s1[8], s1[9]); p.y = cvtpk(s1[10], s1[11]); p.z = cvtpk(s1[12], s1[13]); p.w = cvtpk(s1[14], s1[15]); pb[3] = __builtin_bit_cast(bf16x8, p); }
;             const LAS unsigned char* vb = bb + KB + n * PV + 8 * h;
; #pragma unroll
;             for (int sx = 0; sx < 4; ++sx) {
;                 const s16x4 a0 = *(const LAS s16x4*)(vb + 32 * sx), a1 = *(const LAS s16x4*)(vb + 32 * sx + 16);
;                 const s16x4 b0 = *(const LAS s16x4*)(vb + 32 * PV + 32 * sx), b1 = *(const LAS s16x4*)(vb + 32 * PV + 32 * sx + 16);
;                 o0 = MFMA32(__builtin_shufflevector(a0, a1, 0, 1, 2, 3, 4, 5, 6, 7), pb[sx], o0);
;                 o1 = MFMA32(__builtin_shufflevector(b0, b1, 0, 1, 2, 3, 4, 5, 6, 7), pb[sx], o1);
;             }
.LBB0_196:
	v_cmp_neq_f32_e32 vcc, s79, v115
	s_nop 1
	v_cndmask_b32_e64 v116, v247, -v115, vcc
	v_add_f32_e32 v34, v34, v116
	v_add_f32_e32 v35, v35, v116
	v_add_f32_e32 v50, v50, v116
	v_add_f32_e32 v51, v51, v116
	v_add_f32_e32 v36, v36, v116
	v_add_f32_e32 v37, v37, v116
	v_add_f32_e32 v52, v52, v116
	v_add_f32_e32 v53, v53, v116
	v_exp_f32_e32 v119, v34
	v_exp_f32_e32 v35, v35
	v_exp_f32_e32 v121, v50
	v_exp_f32_e32 v51, v51
	v_exp_f32_e32 v118, v36
	v_exp_f32_e32 v34, v37
	v_exp_f32_e32 v120, v52
	v_exp_f32_e32 v50, v53
	v_add_f32_e32 v38, v38, v116
	v_add_f32_e32 v39, v39, v116
	v_add_f32_e32 v36, v34, v118
	v_add_f32_e32 v37, v35, v119
	v_exp_f32_e32 v123, v39
	v_add_f32_e32 v52, v50, v120
	v_add_f32_e32 v53, v51, v121
	v_add_f32_e32 v40, v40, v116
	v_add_f32_e32 v41, v41, v116
	v_add_f32_e32 v36, v52, v36
	v_add_f32_e32 v37, v53, v37
	v_add_f32_e32 v52, v54, v116
	v_add_f32_e32 v53, v55, v116
	v_exp_f32_e32 v55, v38
	v_exp_f32_e32 v54, v52
	v_exp_f32_e32 v122, v53
	v_add_f32_e32 v52, v56, v116
	v_add_f32_e32 v53, v57, v116
	v_add_f32_e32 v37, 0, v37
	v_exp_f32_e32 v126, v40
	v_add_f32_e32 v38, v122, v54
	v_add_f32_e32 v39, v123, v55
	v_exp_f32_e32 v127, v41
	v_pk_add_f32 v[38:39], v[38:39], v[38:39] op_sel_hi:[0,1]
	v_exp_f32_e32 v128, v52
	v_exp_f32_e32 v129, v53
	v_add_f32_e32 v40, v42, v116
	v_add_f32_e32 v41, v43, v116
	v_add_f32_e32 v42, v58, v116
	v_add_f32_e32 v43, v59, v116
	v_add_f32_e32 v37, v36, v37
	v_exp_f32_e32 v36, v40
	v_exp_f32_e32 v38, v41
	v_exp_f32_e32 v52, v42
	v_exp_f32_e32 v56, v43
	v_add_f32_e32 v53, v127, v126
	v_add_f32_e32 v57, v129, v128
	v_add_f32_e32 v40, v38, v36
	v_add_f32_e32 v41, v39, v37
	v_add_f32_e32 v42, v56, v52
	v_add_f32_e32 v43, v57, v53
	s_nop 0
	v_add_f32_e32 v40, v42, v40
	v_add_f32_e32 v41, v43, v41
	v_add_f32_e32 v42, v44, v116
	v_add_f32_e32 v43, v45, v116
	v_add_f32_e32 v44, v60, v116
	v_add_f32_e32 v45, v61, v116
	v_exp_f32_e32 v59, v42
	v_exp_f32_e32 v61, v43
	v_exp_f32_e32 v58, v44
	v_exp_f32_e32 v60, v45
	v_add_f32_e32 v44, v62, v116
	v_add_f32_e32 v45, v63, v116
	v_pk_add_f32 v[40:41], v[40:41], v[40:41] op_sel_hi:[0,1]
	v_exp_f32_e32 v53, v44
	v_exp_f32_e32 v57, v45
	v_add_f32_e32 v42, v60, v58
	v_add_f32_e32 v43, v61, v59
	s_nop 0
	v_pk_add_f32 v[124:125], v[42:43], v[42:43] op_sel_hi:[0,1]
	v_add_f32_e32 v42, v46, v116
	v_add_f32_e32 v43, v47, v116
	v_add_f32_e32 v117, v57, v53
	v_exp_f32_e32 v37, v42
	v_exp_f32_e32 v39, v43
	v_add_f32_e32 v42, v48, v116
	v_add_f32_e32 v43, v49, v116
	v_add_f32_e32 v44, v64, v116
	v_add_f32_e32 v45, v65, v116
	v_exp_f32_e32 v40, v42
	v_exp_f32_e32 v124, v43
	v_exp_f32_e32 v62, v44
	v_exp_f32_e32 v116, v45
	v_add_f32_e32 v63, v39, v37
	v_add_f32_e32 v42, v124, v40
	v_add_f32_e32 v43, v125, v41
	v_cvt_pk_bf16_f32 v47, v118, v34
	v_add_f32_e32 v44, v116, v62
	v_add_f32_e32 v45, v117, v63
	v_cvt_pk_bf16_f32 v34, v52, v56
	v_add_f32_e32 v42, v44, v42
	v_add_f32_e32 v43, v45, v43
	v_cvt_pk_bf16_f32 v45, v40, v124
	v_cvt_pk_bf16_f32 v40, v54, v122
	v_add3_u32 v54, s4, v188, v164
	v_cvt_pk_bf16_f32 v44, v37, v39
	v_cvt_pk_bf16_f32 v37, v62, v116
	v_add_u32_e32 v62, 0x3000, v54
	v_add_f32_e32 v41, v42, v43
	v_cvt_pk_bf16_f32 v42, v36, v38
	v_cvt_pk_bf16_f32 v38, v121, v51
	v_cvt_pk_bf16_f32 v39, v120, v50
	v_cvt_pk_bf16_f32 v36, v53, v57
	ds_read2_b64 v[50:53], v62 offset0:160 offset1:162
	v_add_u32_e32 v63, 0x2000, v54
	v_cvt_pk_bf16_f32 v46, v119, v35
	v_cvt_pk_bf16_f32 v48, v55, v123
	v_cvt_pk_bf16_f32 v43, v59, v61
	v_cvt_pk_bf16_f32 v35, v58, v60
	ds_read2_b64 v[54:57], v63 offset0:128 offset1:130
	ds_read2_b64 v[58:61], v63 offset0:132 offset1:134
	v_cvt_pk_bf16_f32 v49, v126, v127
	v_add_f32_e32 v113, v113, v41
	v_cvt_pk_bf16_f32 v41, v128, v129
	ds_read2_b64 v[116:119], v62 offset0:164 offset1:166
	ds_read2_b64 v[120:123], v63 offset0:136 offset1:138
	s_waitcnt lgkmcnt(3)
	v_mfma_f32_32x32x16_bf16 v[18:33], v[54:57], v[46:49], v[18:33]
	v_mfma_f32_32x32x16_bf16 v[2:17], v[50:53], v[46:49], v[2:17]
	ds_read2_b64 v[54:57], v62 offset0:168 offset1:170
	ds_read2_b64 v[50:53], v63 offset0:140 offset1:142
	s_waitcnt lgkmcnt(4)
	v_mfma_f32_32x32x16_bf16 v[18:33], v[58:61], v[42:45], v[18:33]
	ds_read2_b64 v[58:61], v62 offset0:172 offset1:174
	s_waitcnt lgkmcnt(4)
	v_mfma_f32_32x32x16_bf16 v[2:17], v[116:119], v[42:45], v[2:17]
	s_waitcnt lgkmcnt(3)
	v_mfma_f32_32x32x16_bf16 v[18:33], v[120:123], v[38:41], v[18:33]
	s_waitcnt lgkmcnt(2)
	v_mfma_f32_32x32x16_bf16 v[2:17], v[54:57], v[38:41], v[2:17]
	s_waitcnt lgkmcnt(1)
	v_mfma_f32_32x32x16_bf16 v[18:33], v[50:53], v[34:37], v[18:33]
	s_waitcnt lgkmcnt(0)
	v_mfma_f32_32x32x16_bf16 v[2:17], v[58:61], v[34:37], v[2:17]
	s_cmp_ge_i32 s8, s14
	s_mov_b64 s[4:5], -1
	s_cbranch_scc0 .LBB0_190

; #define LAS __attribute__((address_space(3)))
; DI unsigned cvtpk(float lo, float hi) { f32x2_t v = {lo, hi}; bf16x2_t b = __builtin_convertvector(v, bf16x2_t); return __builtin_bit_cast(unsigned, b); }
; DI float fexp2(float x) { return __builtin_amdgcn_exp2f(x); }
; #define MFMA32(a, b, c) __builtin_amdgcn_mfma_f32_32x32x16_bf16((a), (b), (c), 0, 0, 0)
;     ...
;             const float mu = (m == -INFINITY) ? 0.f : m;
;             float rs = 0.f;
; #pragma unroll
;             for (int i = 0; i < 16; i += 2) {
;                 f32x2_t a2 = {s0[i], s0[i + 1]}, b2 = {s1[i], s1[i + 1]}; const f32x2_t nm = {-mu, -mu};
;                 a2 = a2 + nm; b2 = b2 + nm;
;                 s0[i] = fexp2(a2.x); s0[i + 1] = fexp2(a2.y); s1[i] = fexp2(b2.x); s1[i + 1] = fexp2(b2.y);
;                 rs += (s0[i] + s0[i + 1]) + (s1[i] + s1[i + 1]); }
;             l += rs;
;             bf16x8 pb[4];
;             { u32x4 p; p.x = cvtpk(s0[0], s0[1]); p.y = cvtpk(s0[2], s0[3]); p.z = cvtpk(s0[4], s0[5]); p.w = cvtpk(s0[6], s0[7]); pb[0] = __builtin_bit_cast(bf16x8, p);
;               p.x = cvtpk(s0[8], s0[9]); p.y = cvtpk(s0[10], s0[11]); p.z = cvtpk(s0[12], s0[13]); p.w = cvtpk(s0[14], s0[15]); pb[1] = __builtin_bit_cast(bf16x8, p);
;               p.x = cvtpk(s1[0], s1[1]); p.y = cvtpk(s1[2], s1[3]); p.z = cvtpk(s1[4], s1[5]); p.w = cvtpk(s1[6], s1[7]); pb[2] = __builtin_bit_cast(bf16x8, p);
;               p.x = cvtpk(s1[8], s1[9]); p.y = cvtpk(s1[10], s1[11]); p.z = cvtpk(s1[12], s1[13]); p.w = cvtpk(s1[14], s1[15]); pb[3] = __builtin_bit_cast(bf16x8, p); }
;             const LAS unsigned char* vb = bb + KB + n * PV + 8 * h;
; #pragma unroll
;             for (int sx = 0; sx < 4; ++sx) {
;                 const s16x4 a0 = *(const LAS s16x4*)(vb + 32 * sx), a1 = *(const LAS s16x4*)(vb + 32 * sx + 16);
;                 const s16x4 b0 = *(const LAS s16x4*)(vb + 32 * PV + 32 * sx), b1 = *(const LAS s16x4*)(vb + 32 * PV + 32 * sx + 16);
;                 o0 = MFMA32(__builtin_shufflevector(a0, a1, 0, 1, 2, 3, 4, 5, 6, 7), pb[sx], o0);
;                 o1 = MFMA32(__builtin_shufflevector(b0, b1, 0, 1, 2, 3, 4, 5, 6, 7), pb[sx], o1);
;             }
.LBB0_253:
	v_cmp_neq_f32_e32 vcc, s79, v145
	s_nop 1
	v_cndmask_b32_e64 v146, v247, -v145, vcc
	v_add_f32_e32 v50, v50, v146
	v_add_f32_e32 v51, v51, v146
	v_add_f32_e32 v34, v34, v146
	v_add_f32_e32 v35, v35, v146
	v_add_f32_e32 v52, v52, v146
	v_add_f32_e32 v53, v53, v146
	v_add_f32_e32 v36, v36, v146
	v_add_f32_e32 v37, v37, v146
	v_exp_f32_e32 v149, v50
	v_exp_f32_e32 v51, v51
	v_exp_f32_e32 v151, v34
	v_exp_f32_e32 v35, v35
	v_exp_f32_e32 v148, v52
	v_exp_f32_e32 v50, v53
	v_exp_f32_e32 v150, v36
	v_exp_f32_e32 v34, v37
	v_add_f32_e32 v38, v38, v146
	v_add_f32_e32 v39, v39, v146
	v_add_f32_e32 v36, v50, v148
	v_add_f32_e32 v37, v51, v149
	v_add_f32_e32 v56, v56, v146
	v_add_f32_e32 v57, v57, v146
	v_add_f32_e32 v52, v34, v150
	v_add_f32_e32 v53, v35, v151
	v_add_f32_e32 v40, v40, v146
	v_add_f32_e32 v41, v41, v146
	v_add_f32_e32 v36, v52, v36
	v_add_f32_e32 v37, v53, v37
	v_add_f32_e32 v52, v54, v146
	v_add_f32_e32 v53, v55, v146
	v_exp_f32_e32 v54, v38
	v_exp_f32_e32 v55, v52
	v_exp_f32_e32 v53, v53
	v_exp_f32_e32 v52, v39
	v_add_f32_e32 v37, 0, v37
	v_exp_f32_e32 v156, v56
	v_exp_f32_e32 v157, v57
	v_add_f32_e32 v38, v52, v54
	v_add_f32_e32 v39, v53, v55
	v_exp_f32_e32 v158, v40
	v_pk_add_f32 v[38:39], v[38:39], v[38:39] op_sel_hi:[0,1]
	v_exp_f32_e32 v159, v41
	v_add_f32_e32 v40, v58, v146
	v_add_f32_e32 v41, v59, v146
	v_add_f32_e32 v42, v42, v146
	v_add_f32_e32 v43, v43, v146
	v_add_f32_e32 v37, v36, v37
	v_exp_f32_e32 v36, v40
	v_exp_f32_e32 v38, v41
	v_exp_f32_e32 v56, v42
	v_exp_f32_e32 v152, v43
	v_add_f32_e32 v57, v157, v156
	v_add_f32_e32 v153, v159, v158
	v_add_f32_e32 v40, v38, v36
	v_add_f32_e32 v41, v39, v37
	v_add_f32_e32 v42, v152, v56
	v_add_f32_e32 v43, v153, v57
	v_add_f32_e32 v44, v44, v146
	v_add_f32_e32 v45, v45, v146
	v_add_f32_e32 v40, v42, v40
	v_add_f32_e32 v41, v43, v41
	v_add_f32_e32 v42, v60, v146
	v_add_f32_e32 v43, v61, v146
	v_exp_f32_e32 v58, v44
	v_exp_f32_e32 v59, v42
	v_exp_f32_e32 v61, v43
	v_exp_f32_e32 v60, v45
	v_add_f32_e32 v44, v46, v146
	v_add_f32_e32 v45, v47, v146
	v_pk_add_f32 v[40:41], v[40:41], v[40:41] op_sel_hi:[0,1]
	v_exp_f32_e32 v57, v44
	v_exp_f32_e32 v153, v45
	v_add_f32_e32 v42, v60, v58
	v_add_f32_e32 v43, v61, v59
	v_cvt_pk_bf16_f32 v46, v149, v51
	v_pk_add_f32 v[154:155], v[42:43], v[42:43] op_sel_hi:[0,1]
	v_add_f32_e32 v42, v62, v146
	v_add_f32_e32 v43, v63, v146
	v_add_f32_e32 v147, v153, v57
	v_exp_f32_e32 v37, v42
	v_exp_f32_e32 v39, v43
	v_add_f32_e32 v42, v64, v146
	v_add_f32_e32 v43, v65, v146
	v_add_f32_e32 v44, v48, v146
	v_add_f32_e32 v45, v49, v146
	v_exp_f32_e32 v40, v42
	v_exp_f32_e32 v154, v43
	v_exp_f32_e32 v62, v44
	v_exp_f32_e32 v146, v45
	v_add_f32_e32 v63, v39, v37
	v_add_f32_e32 v42, v154, v40
	v_add_f32_e32 v43, v155, v41
	v_cvt_pk_bf16_f32 v47, v148, v50
	v_add_f32_e32 v44, v146, v62
	v_add_f32_e32 v45, v147, v63
	v_cvt_pk_bf16_f32 v48, v55, v53
	v_add_f32_e32 v42, v44, v42
	v_add_f32_e32 v43, v45, v43
	v_cvt_pk_bf16_f32 v45, v40, v154
	v_cvt_pk_bf16_f32 v40, v54, v52
	v_add3_u32 v54, s10, v119, v116
	v_cvt_pk_bf16_f32 v44, v37, v39
	v_cvt_pk_bf16_f32 v37, v62, v146
	v_add_u32_e32 v62, 0x5000, v54
	ds_read2_b64 v[50:53], v62 offset0:160 offset1:162
	v_add_u32_e32 v63, 0x4000, v54
	v_add_f32_e32 v41, v42, v43
	v_cvt_pk_bf16_f32 v42, v36, v38
	v_cvt_pk_bf16_f32 v43, v59, v61
	v_cvt_pk_bf16_f32 v38, v151, v35
	v_cvt_pk_bf16_f32 v39, v150, v34
	v_cvt_pk_bf16_f32 v34, v56, v152
	v_cvt_pk_bf16_f32 v35, v58, v60
	v_cvt_pk_bf16_f32 v36, v57, v153
	ds_read2_b64 v[54:57], v63 offset0:128 offset1:130
	ds_read2_b64 v[58:61], v63 offset0:132 offset1:134
	v_cvt_pk_bf16_f32 v49, v156, v157
	v_add_f32_e32 v144, v144, v41
	v_cvt_pk_bf16_f32 v41, v158, v159
	ds_read2_b64 v[146:149], v62 offset0:164 offset1:166
	ds_read2_b64 v[150:153], v63 offset0:136 offset1:138
	s_waitcnt lgkmcnt(3)
	v_mfma_f32_32x32x16_bf16 v[18:33], v[54:57], v[46:49], v[18:33]
	v_mfma_f32_32x32x16_bf16 v[2:17], v[50:53], v[46:49], v[2:17]
	ds_read2_b64 v[54:57], v62 offset0:168 offset1:170
	ds_read2_b64 v[50:53], v63 offset0:140 offset1:142
	s_waitcnt lgkmcnt(4)
	v_mfma_f32_32x32x16_bf16 v[18:33], v[58:61], v[42:45], v[18:33]
	ds_read2_b64 v[58:61], v62 offset0:172 offset1:174
	s_waitcnt lgkmcnt(4)
	v_mfma_f32_32x32x16_bf16 v[2:17], v[146:149], v[42:45], v[2:17]
	s_waitcnt lgkmcnt(3)
	v_mfma_f32_32x32x16_bf16 v[18:33], v[150:153], v[38:41], v[18:33]
	s_waitcnt lgkmcnt(2)
	v_mfma_f32_32x32x16_bf16 v[2:17], v[54:57], v[38:41], v[2:17]
	s_waitcnt lgkmcnt(1)
	v_mfma_f32_32x32x16_bf16 v[18:33], v[50:53], v[34:37], v[18:33]
	s_waitcnt lgkmcnt(0)
	v_mfma_f32_32x32x16_bf16 v[2:17], v[58:61], v[34:37], v[2:17]
	s_cmp_ge_u32 s45, s37
	s_cbranch_scc1 .LBB0_259

; #define LAS __attribute__((address_space(3)))
; DI unsigned cvtpk(float lo, float hi) { f32x2_t v = {lo, hi}; bf16x2_t b = __builtin_convertvector(v, bf16x2_t); return __builtin_bit_cast(unsigned, b); }
; DI float fexp2(float x) { return __builtin_amdgcn_exp2f(x); }
; #define MFMA32(a, b, c) __builtin_amdgcn_mfma_f32_32x32x16_bf16((a), (b), (c), 0, 0, 0)
;     ...
;             const float mu = (m == -INFINITY) ? 0.f : m;
;             float rs = 0.f;
; #pragma unroll
;             for (int i = 0; i < 16; i += 2) {
;                 f32x2_t a2 = {s0[i], s0[i + 1]}, b2 = {s1[i], s1[i + 1]}; const f32x2_t nm = {-mu, -mu};
;                 a2 = a2 + nm; b2 = b2 + nm;
;                 s0[i] = fexp2(a2.x); s0[i + 1] = fexp2(a2.y); s1[i] = fexp2(b2.x); s1[i + 1] = fexp2(b2.y);
;                 rs += (s0[i] + s0[i + 1]) + (s1[i] + s1[i + 1]); }
;             l += rs;
;             bf16x8 pb[4];
;             { u32x4 p; p.x = cvtpk(s0[0], s0[1]); p.y = cvtpk(s0[2], s0[3]); p.z = cvtpk(s0[4], s0[5]); p.w = cvtpk(s0[6], s0[7]); pb[0] = __builtin_bit_cast(bf16x8, p);
;               p.x = cvtpk(s0[8], s0[9]); p.y = cvtpk(s0[10], s0[11]); p.z = cvtpk(s0[12], s0[13]); p.w = cvtpk(s0[14], s0[15]); pb[1] = __builtin_bit_cast(bf16x8, p);
;               p.x = cvtpk(s1[0], s1[1]); p.y = cvtpk(s1[2], s1[3]); p.z = cvtpk(s1[4], s1[5]); p.w = cvtpk(s1[6], s1[7]); pb[2] = __builtin_bit_cast(bf16x8, p);
;               p.x = cvtpk(s1[8], s1[9]); p.y = cvtpk(s1[10], s1[11]); p.z = cvtpk(s1[12], s1[13]); p.w = cvtpk(s1[14], s1[15]); pb[3] = __builtin_bit_cast(bf16x8, p); }
;             const LAS unsigned char* vb = bb + KB + n * PV + 8 * h;
; #pragma unroll
;             for (int sx = 0; sx < 4; ++sx) {
;                 const s16x4 a0 = *(const LAS s16x4*)(vb + 32 * sx), a1 = *(const LAS s16x4*)(vb + 32 * sx + 16);
;                 const s16x4 b0 = *(const LAS s16x4*)(vb + 32 * PV + 32 * sx), b1 = *(const LAS s16x4*)(vb + 32 * PV + 32 * sx + 16);
;                 o0 = MFMA32(__builtin_shufflevector(a0, a1, 0, 1, 2, 3, 4, 5, 6, 7), pb[sx], o0);
;                 o1 = MFMA32(__builtin_shufflevector(b0, b1, 0, 1, 2, 3, 4, 5, 6, 7), pb[sx], o1);
;             }
.LBB0_319:
	v_cmp_neq_f32_e32 vcc, s79, v112
	s_nop 1
	v_cndmask_b32_e64 v124, v247, -v112, vcc
	v_add_f32_e32 v50, v50, v124
	v_add_f32_e32 v51, v51, v124
	v_add_f32_e32 v34, v34, v124
	v_add_f32_e32 v35, v35, v124
	v_add_f32_e32 v52, v52, v124
	v_add_f32_e32 v53, v53, v124
	v_add_f32_e32 v36, v36, v124
	v_add_f32_e32 v37, v37, v124
	v_exp_f32_e32 v127, v50
	v_exp_f32_e32 v51, v51
	v_exp_f32_e32 v129, v34
	v_exp_f32_e32 v35, v35
	v_exp_f32_e32 v126, v52
	v_exp_f32_e32 v50, v53
	v_exp_f32_e32 v128, v36
	v_exp_f32_e32 v34, v37
	v_add_f32_e32 v38, v38, v124
	v_add_f32_e32 v39, v39, v124
	v_add_f32_e32 v36, v50, v126
	v_add_f32_e32 v37, v51, v127
	v_add_f32_e32 v56, v56, v124
	v_add_f32_e32 v57, v57, v124
	v_add_f32_e32 v52, v34, v128
	v_add_f32_e32 v53, v35, v129
	v_add_f32_e32 v40, v40, v124
	v_add_f32_e32 v41, v41, v124
	v_add_f32_e32 v36, v52, v36
	v_add_f32_e32 v37, v53, v37
	v_add_f32_e32 v52, v54, v124
	v_add_f32_e32 v53, v55, v124
	v_exp_f32_e32 v54, v38
	v_exp_f32_e32 v55, v52
	v_exp_f32_e32 v53, v53
	v_exp_f32_e32 v52, v39
	v_add_f32_e32 v37, 0, v37
	v_exp_f32_e32 v123, v56
	v_exp_f32_e32 v134, v57
	v_add_f32_e32 v38, v52, v54
	v_add_f32_e32 v39, v53, v55
	v_exp_f32_e32 v135, v40
	v_pk_add_f32 v[38:39], v[38:39], v[38:39] op_sel_hi:[0,1]
	v_exp_f32_e32 v136, v41
	v_add_f32_e32 v40, v58, v124
	v_add_f32_e32 v41, v59, v124
	v_add_f32_e32 v42, v42, v124
	v_add_f32_e32 v43, v43, v124
	v_add_f32_e32 v37, v36, v37
	v_exp_f32_e32 v36, v40
	v_exp_f32_e32 v38, v41
	v_exp_f32_e32 v56, v42
	v_exp_f32_e32 v130, v43
	v_add_f32_e32 v57, v134, v123
	v_add_f32_e32 v131, v136, v135
	v_add_f32_e32 v40, v38, v36
	v_add_f32_e32 v41, v39, v37
	v_add_f32_e32 v42, v130, v56
	v_add_f32_e32 v43, v131, v57
	v_add_f32_e32 v44, v44, v124
	v_add_f32_e32 v45, v45, v124
	v_add_f32_e32 v40, v42, v40
	v_add_f32_e32 v41, v43, v41
	v_add_f32_e32 v42, v60, v124
	v_add_f32_e32 v43, v61, v124
	v_exp_f32_e32 v58, v44
	v_exp_f32_e32 v59, v42
	v_exp_f32_e32 v61, v43
	v_exp_f32_e32 v60, v45
	v_add_f32_e32 v44, v46, v124
	v_add_f32_e32 v45, v47, v124
	v_pk_add_f32 v[40:41], v[40:41], v[40:41] op_sel_hi:[0,1]
	v_exp_f32_e32 v57, v44
	v_exp_f32_e32 v131, v45
	v_add_f32_e32 v42, v60, v58
	v_add_f32_e32 v43, v61, v59
	v_cvt_pk_bf16_f32 v46, v127, v51
	v_pk_add_f32 v[132:133], v[42:43], v[42:43] op_sel_hi:[0,1]
	v_add_f32_e32 v42, v62, v124
	v_add_f32_e32 v43, v63, v124
	v_add_f32_e32 v125, v131, v57
	v_exp_f32_e32 v37, v42
	v_exp_f32_e32 v39, v43
	v_add_f32_e32 v42, v64, v124
	v_add_f32_e32 v43, v65, v124
	v_add_f32_e32 v44, v48, v124
	v_add_f32_e32 v45, v49, v124
	v_exp_f32_e32 v40, v42
	v_exp_f32_e32 v132, v43
	v_exp_f32_e32 v62, v44
	v_exp_f32_e32 v124, v45
	v_add_f32_e32 v63, v39, v37
	v_add_f32_e32 v42, v132, v40
	v_add_f32_e32 v43, v133, v41
	v_cvt_pk_bf16_f32 v47, v126, v50
	v_add_f32_e32 v44, v124, v62
	v_add_f32_e32 v45, v125, v63
	v_cvt_pk_bf16_f32 v48, v55, v53
	v_add_f32_e32 v42, v44, v42
	v_add_f32_e32 v43, v45, v43
	v_cvt_pk_bf16_f32 v45, v40, v132
	v_cvt_pk_bf16_f32 v40, v54, v52
	v_add3_u32 v54, s36, v119, v116
	v_cvt_pk_bf16_f32 v44, v37, v39
	v_cvt_pk_bf16_f32 v37, v62, v124
	v_add_u32_e32 v62, 0x3000, v54
	ds_read2_b64 v[50:53], v62 offset0:160 offset1:162
	v_add_u32_e32 v63, 0x2000, v54
	v_add_f32_e32 v41, v42, v43
	v_cvt_pk_bf16_f32 v42, v36, v38
	v_cvt_pk_bf16_f32 v43, v59, v61
	v_cvt_pk_bf16_f32 v38, v129, v35
	v_cvt_pk_bf16_f32 v39, v128, v34
	v_cvt_pk_bf16_f32 v34, v56, v130
	v_cvt_pk_bf16_f32 v35, v58, v60
	v_cvt_pk_bf16_f32 v36, v57, v131
	ds_read2_b64 v[54:57], v63 offset0:128 offset1:130
	ds_read2_b64 v[58:61], v63 offset0:132 offset1:134
	v_cvt_pk_bf16_f32 v49, v123, v134
	v_add_f32_e32 v105, v105, v41
	v_cvt_pk_bf16_f32 v41, v135, v136
	ds_read2_b64 v[124:127], v62 offset0:164 offset1:166
	ds_read2_b64 v[128:131], v63 offset0:136 offset1:138
	s_waitcnt lgkmcnt(3)
	v_mfma_f32_32x32x16_bf16 v[18:33], v[54:57], v[46:49], v[18:33]
	v_mfma_f32_32x32x16_bf16 v[2:17], v[50:53], v[46:49], v[2:17]
	ds_read2_b64 v[54:57], v62 offset0:168 offset1:170
	ds_read2_b64 v[50:53], v63 offset0:140 offset1:142
	s_waitcnt lgkmcnt(4)
	v_mfma_f32_32x32x16_bf16 v[18:33], v[58:61], v[42:45], v[18:33]
	ds_read2_b64 v[58:61], v62 offset0:172 offset1:174
	s_waitcnt lgkmcnt(4)
	v_mfma_f32_32x32x16_bf16 v[2:17], v[124:127], v[42:45], v[2:17]
	s_waitcnt lgkmcnt(3)
	v_mfma_f32_32x32x16_bf16 v[18:33], v[128:131], v[38:41], v[18:33]
	s_waitcnt lgkmcnt(2)
	v_mfma_f32_32x32x16_bf16 v[2:17], v[54:57], v[38:41], v[2:17]
	s_waitcnt lgkmcnt(1)
	v_mfma_f32_32x32x16_bf16 v[18:33], v[50:53], v[34:37], v[18:33]
	s_waitcnt lgkmcnt(0)
	v_mfma_f32_32x32x16_bf16 v[2:17], v[58:61], v[34:37], v[2:17]

; #define LAS __attribute__((address_space(3)))
; DI unsigned cvtpk(float lo, float hi) { f32x2_t v = {lo, hi}; bf16x2_t b = __builtin_convertvector(v, bf16x2_t); return __builtin_bit_cast(unsigned, b); }
; DI float fexp2(float x) { return __builtin_amdgcn_exp2f(x); }
; #define MFMA32(a, b, c) __builtin_amdgcn_mfma_f32_32x32x16_bf16((a), (b), (c), 0, 0, 0)
;     ...
;             const float mu = (m == -INFINITY) ? 0.f : m;
;             float rs = 0.f;
; #pragma unroll
;             for (int i = 0; i < 16; i += 2) {
;                 f32x2_t a2 = {s0[i], s0[i + 1]}, b2 = {s1[i], s1[i + 1]}; const f32x2_t nm = {-mu, -mu};
;                 a2 = a2 + nm; b2 = b2 + nm;
;                 s0[i] = fexp2(a2.x); s0[i + 1] = fexp2(a2.y); s1[i] = fexp2(b2.x); s1[i + 1] = fexp2(b2.y);
;                 rs += (s0[i] + s0[i + 1]) + (s1[i] + s1[i + 1]); }
;             l += rs;
;             bf16x8 pb[4];
;             { u32x4 p; p.x = cvtpk(s0[0], s0[1]); p.y = cvtpk(s0[2], s0[3]); p.z = cvtpk(s0[4], s0[5]); p.w = cvtpk(s0[6], s0[7]); pb[0] = __builtin_bit_cast(bf16x8, p);
;               p.x = cvtpk(s0[8], s0[9]); p.y = cvtpk(s0[10], s0[11]); p.z = cvtpk(s0[12], s0[13]); p.w = cvtpk(s0[14], s0[15]); pb[1] = __builtin_bit_cast(bf16x8, p);
;               p.x = cvtpk(s1[0], s1[1]); p.y = cvtpk(s1[2], s1[3]); p.z = cvtpk(s1[4], s1[5]); p.w = cvtpk(s1[6], s1[7]); pb[2] = __builtin_bit_cast(bf16x8, p);
;               p.x = cvtpk(s1[8], s1[9]); p.y = cvtpk(s1[10], s1[11]); p.z = cvtpk(s1[12], s1[13]); p.w = cvtpk(s1[14], s1[15]); pb[3] = __builtin_bit_cast(bf16x8, p); }
;             const LAS unsigned char* vb = bb + KB + n * PV + 8 * h;
; #pragma unroll
;             for (int sx = 0; sx < 4; ++sx) {
;                 const s16x4 a0 = *(const LAS s16x4*)(vb + 32 * sx), a1 = *(const LAS s16x4*)(vb + 32 * sx + 16);
;                 const s16x4 b0 = *(const LAS s16x4*)(vb + 32 * PV + 32 * sx), b1 = *(const LAS s16x4*)(vb + 32 * PV + 32 * sx + 16);
;                 o0 = MFMA32(__builtin_shufflevector(a0, a1, 0, 1, 2, 3, 4, 5, 6, 7), pb[sx], o0);
;                 o1 = MFMA32(__builtin_shufflevector(b0, b1, 0, 1, 2, 3, 4, 5, 6, 7), pb[sx], o1);
;             }
.LBB0_333:
	v_cmp_neq_f32_e32 vcc, s79, v112
	s_nop 1
	v_cndmask_b32_e64 v124, v247, -v112, vcc
	v_add_f32_e32 v34, v34, v124
	v_add_f32_e32 v35, v35, v124
	v_add_f32_e32 v50, v50, v124
	v_add_f32_e32 v51, v51, v124
	v_add_f32_e32 v36, v36, v124
	v_add_f32_e32 v37, v37, v124
	v_add_f32_e32 v52, v52, v124
	v_add_f32_e32 v53, v53, v124
	v_exp_f32_e32 v127, v34
	v_exp_f32_e32 v35, v35
	v_exp_f32_e32 v129, v50
	v_exp_f32_e32 v51, v51
	v_exp_f32_e32 v126, v36
	v_exp_f32_e32 v34, v37
	v_exp_f32_e32 v128, v52
	v_exp_f32_e32 v50, v53
	v_add_f32_e32 v38, v38, v124
	v_add_f32_e32 v39, v39, v124
	v_add_f32_e32 v36, v34, v126
	v_add_f32_e32 v37, v35, v127
	v_exp_f32_e32 v131, v39
	v_add_f32_e32 v52, v50, v128
	v_add_f32_e32 v53, v51, v129
	v_add_f32_e32 v40, v40, v124
	v_add_f32_e32 v41, v41, v124
	v_add_f32_e32 v36, v52, v36
	v_add_f32_e32 v37, v53, v37
	v_add_f32_e32 v52, v54, v124
	v_add_f32_e32 v53, v55, v124
	v_exp_f32_e32 v55, v38
	v_exp_f32_e32 v54, v52
	v_exp_f32_e32 v130, v53
	v_add_f32_e32 v52, v56, v124
	v_add_f32_e32 v53, v57, v124
	v_add_f32_e32 v37, 0, v37
	v_exp_f32_e32 v123, v40
	v_add_f32_e32 v38, v130, v54
	v_add_f32_e32 v39, v131, v55
	v_exp_f32_e32 v134, v41
	v_pk_add_f32 v[38:39], v[38:39], v[38:39] op_sel_hi:[0,1]
	v_exp_f32_e32 v135, v52
	v_exp_f32_e32 v136, v53
	v_add_f32_e32 v40, v42, v124
	v_add_f32_e32 v41, v43, v124
	v_add_f32_e32 v42, v58, v124
	v_add_f32_e32 v43, v59, v124
	v_add_f32_e32 v37, v36, v37
	v_exp_f32_e32 v36, v40
	v_exp_f32_e32 v38, v41
	v_exp_f32_e32 v52, v42
	v_exp_f32_e32 v56, v43
	v_add_f32_e32 v53, v134, v123
	v_add_f32_e32 v57, v136, v135
	v_add_f32_e32 v40, v38, v36
	v_add_f32_e32 v41, v39, v37
	v_add_f32_e32 v42, v56, v52
	v_add_f32_e32 v43, v57, v53
	s_nop 0
	v_add_f32_e32 v40, v42, v40
	v_add_f32_e32 v41, v43, v41
	v_add_f32_e32 v42, v44, v124
	v_add_f32_e32 v43, v45, v124
	v_add_f32_e32 v44, v60, v124
	v_add_f32_e32 v45, v61, v124
	v_exp_f32_e32 v59, v42
	v_exp_f32_e32 v61, v43
	v_exp_f32_e32 v58, v44
	v_exp_f32_e32 v60, v45
	v_add_f32_e32 v44, v62, v124
	v_add_f32_e32 v45, v63, v124
	v_pk_add_f32 v[40:41], v[40:41], v[40:41] op_sel_hi:[0,1]
	v_exp_f32_e32 v53, v44
	v_exp_f32_e32 v57, v45
	v_add_f32_e32 v42, v60, v58
	v_add_f32_e32 v43, v61, v59
	s_nop 0
	v_pk_add_f32 v[132:133], v[42:43], v[42:43] op_sel_hi:[0,1]
	v_add_f32_e32 v42, v46, v124
	v_add_f32_e32 v43, v47, v124
	v_add_f32_e32 v125, v57, v53
	v_exp_f32_e32 v37, v42
	v_exp_f32_e32 v39, v43
	v_add_f32_e32 v42, v48, v124
	v_add_f32_e32 v43, v49, v124
	v_add_f32_e32 v44, v64, v124
	v_add_f32_e32 v45, v65, v124
	v_exp_f32_e32 v40, v42
	v_exp_f32_e32 v132, v43
	v_exp_f32_e32 v62, v44
	v_exp_f32_e32 v124, v45
	v_add_f32_e32 v63, v39, v37
	v_add_f32_e32 v42, v132, v40
	v_add_f32_e32 v43, v133, v41
	v_cvt_pk_bf16_f32 v47, v126, v34
	v_add_f32_e32 v44, v124, v62
	v_add_f32_e32 v45, v125, v63
	v_cvt_pk_bf16_f32 v34, v52, v56
	v_add_f32_e32 v42, v44, v42
	v_add_f32_e32 v43, v45, v43
	v_cvt_pk_bf16_f32 v45, v40, v132
	v_cvt_pk_bf16_f32 v40, v54, v130
	v_add3_u32 v54, s43, v119, v116
	v_cvt_pk_bf16_f32 v44, v37, v39
	v_cvt_pk_bf16_f32 v37, v62, v124
	v_add_u32_e32 v62, 0x3000, v54
	v_add_f32_e32 v41, v42, v43
	v_cvt_pk_bf16_f32 v42, v36, v38
	v_cvt_pk_bf16_f32 v38, v129, v51
	v_cvt_pk_bf16_f32 v39, v128, v50
	v_cvt_pk_bf16_f32 v36, v53, v57
	ds_read2_b64 v[50:53], v62 offset0:160 offset1:162
	v_add_u32_e32 v63, 0x2000, v54
	v_cvt_pk_bf16_f32 v46, v127, v35
	v_cvt_pk_bf16_f32 v48, v55, v131
	v_cvt_pk_bf16_f32 v43, v59, v61
	v_cvt_pk_bf16_f32 v35, v58, v60
	ds_read2_b64 v[54:57], v63 offset0:128 offset1:130
	ds_read2_b64 v[58:61], v63 offset0:132 offset1:134
	v_cvt_pk_bf16_f32 v49, v123, v134
	v_add_f32_e32 v105, v105, v41
	v_cvt_pk_bf16_f32 v41, v135, v136
	ds_read2_b64 v[124:127], v62 offset0:164 offset1:166
	ds_read2_b64 v[128:131], v63 offset0:136 offset1:138
	s_waitcnt lgkmcnt(3)
	v_mfma_f32_32x32x16_bf16 v[18:33], v[54:57], v[46:49], v[18:33]
	v_mfma_f32_32x32x16_bf16 v[2:17], v[50:53], v[46:49], v[2:17]
	ds_read2_b64 v[54:57], v62 offset0:168 offset1:170
	ds_read2_b64 v[50:53], v63 offset0:140 offset1:142
	s_waitcnt lgkmcnt(4)
	v_mfma_f32_32x32x16_bf16 v[18:33], v[58:61], v[42:45], v[18:33]
	ds_read2_b64 v[58:61], v62 offset0:172 offset1:174
	s_waitcnt lgkmcnt(4)
	v_mfma_f32_32x32x16_bf16 v[2:17], v[124:127], v[42:45], v[2:17]
	s_waitcnt lgkmcnt(3)
	v_mfma_f32_32x32x16_bf16 v[18:33], v[128:131], v[38:41], v[18:33]
	s_waitcnt lgkmcnt(2)
	v_mfma_f32_32x32x16_bf16 v[2:17], v[54:57], v[38:41], v[2:17]
	s_waitcnt lgkmcnt(1)
	v_mfma_f32_32x32x16_bf16 v[18:33], v[50:53], v[34:37], v[18:33]
	s_waitcnt lgkmcnt(0)
	v_mfma_f32_32x32x16_bf16 v[2:17], v[58:61], v[34:37], v[2:17]

; #define LAS __attribute__((address_space(3)))
; DI unsigned cvtpk(float lo, float hi) { f32x2_t v = {lo, hi}; bf16x2_t b = __builtin_convertvector(v, bf16x2_t); return __builtin_bit_cast(unsigned, b); }
; DI float fexp2(float x) { return __builtin_amdgcn_exp2f(x); }
; #define MFMA32(a, b, c) __builtin_amdgcn_mfma_f32_32x32x16_bf16((a), (b), (c), 0, 0, 0)
;     ...
;             const float mu = (m == -INFINITY) ? 0.f : m;
;             float rs = 0.f;
; #pragma unroll
;             for (int i = 0; i < 16; i += 2) {
;                 f32x2_t a2 = {s0[i], s0[i + 1]}, b2 = {s1[i], s1[i + 1]}; const f32x2_t nm = {-mu, -mu};
;                 a2 = a2 + nm; b2 = b2 + nm;
;                 s0[i] = fexp2(a2.x); s0[i + 1] = fexp2(a2.y); s1[i] = fexp2(b2.x); s1[i + 1] = fexp2(b2.y);
;                 rs += (s0[i] + s0[i + 1]) + (s1[i] + s1[i + 1]); }
;             l += rs;
;             bf16x8 pb[4];
;             { u32x4 p; p.x = cvtpk(s0[0], s0[1]); p.y = cvtpk(s0[2], s0[3]); p.z = cvtpk(s0[4], s0[5]); p.w = cvtpk(s0[6], s0[7]); pb[0] = __builtin_bit_cast(bf16x8, p);
;               p.x = cvtpk(s0[8], s0[9]); p.y = cvtpk(s0[10], s0[11]); p.z = cvtpk(s0[12], s0[13]); p.w = cvtpk(s0[14], s0[15]); pb[1] = __builtin_bit_cast(bf16x8, p);
;               p.x = cvtpk(s1[0], s1[1]); p.y = cvtpk(s1[2], s1[3]); p.z = cvtpk(s1[4], s1[5]); p.w = cvtpk(s1[6], s1[7]); pb[2] = __builtin_bit_cast(bf16x8, p);
;               p.x = cvtpk(s1[8], s1[9]); p.y = cvtpk(s1[10], s1[11]); p.z = cvtpk(s1[12], s1[13]); p.w = cvtpk(s1[14], s1[15]); pb[3] = __builtin_bit_cast(bf16x8, p); }
;             const LAS unsigned char* vb = bb + KB + n * PV + 8 * h;
; #pragma unroll
;             for (int sx = 0; sx < 4; ++sx) {
;                 const s16x4 a0 = *(const LAS s16x4*)(vb + 32 * sx), a1 = *(const LAS s16x4*)(vb + 32 * sx + 16);
;                 const s16x4 b0 = *(const LAS s16x4*)(vb + 32 * PV + 32 * sx), b1 = *(const LAS s16x4*)(vb + 32 * PV + 32 * sx + 16);
;                 o0 = MFMA32(__builtin_shufflevector(a0, a1, 0, 1, 2, 3, 4, 5, 6, 7), pb[sx], o0);
;                 o1 = MFMA32(__builtin_shufflevector(b0, b1, 0, 1, 2, 3, 4, 5, 6, 7), pb[sx], o1);
;             }
.LBB0_353:
	v_cmp_neq_f32_e32 vcc, s79, v112
	s_nop 1
	v_cndmask_b32_e64 v124, v247, -v112, vcc
	v_add_f32_e32 v34, v34, v124
	v_add_f32_e32 v35, v35, v124
	v_add_f32_e32 v50, v50, v124
	v_add_f32_e32 v51, v51, v124
	v_add_f32_e32 v36, v36, v124
	v_add_f32_e32 v37, v37, v124
	v_add_f32_e32 v52, v52, v124
	v_add_f32_e32 v53, v53, v124
	v_exp_f32_e32 v127, v34
	v_exp_f32_e32 v35, v35
	v_exp_f32_e32 v129, v50
	v_exp_f32_e32 v51, v51
	v_exp_f32_e32 v126, v36
	v_exp_f32_e32 v34, v37
	v_exp_f32_e32 v128, v52
	v_exp_f32_e32 v50, v53
	v_add_f32_e32 v38, v38, v124
	v_add_f32_e32 v39, v39, v124
	v_add_f32_e32 v36, v34, v126
	v_add_f32_e32 v37, v35, v127
	v_exp_f32_e32 v131, v39
	v_add_f32_e32 v52, v50, v128
	v_add_f32_e32 v53, v51, v129
	v_add_f32_e32 v40, v40, v124
	v_add_f32_e32 v41, v41, v124
	v_add_f32_e32 v36, v52, v36
	v_add_f32_e32 v37, v53, v37
	v_add_f32_e32 v52, v54, v124
	v_add_f32_e32 v53, v55, v124
	v_exp_f32_e32 v55, v38
	v_exp_f32_e32 v54, v52
	v_exp_f32_e32 v130, v53
	v_add_f32_e32 v52, v56, v124
	v_add_f32_e32 v53, v57, v124
	v_add_f32_e32 v37, 0, v37
	v_exp_f32_e32 v123, v40
	v_add_f32_e32 v38, v130, v54
	v_add_f32_e32 v39, v131, v55
	v_exp_f32_e32 v134, v41
	v_pk_add_f32 v[38:39], v[38:39], v[38:39] op_sel_hi:[0,1]
	v_exp_f32_e32 v135, v52
	v_exp_f32_e32 v136, v53
	v_add_f32_e32 v40, v42, v124
	v_add_f32_e32 v41, v43, v124
	v_add_f32_e32 v42, v58, v124
	v_add_f32_e32 v43, v59, v124
	v_add_f32_e32 v37, v36, v37
	v_exp_f32_e32 v36, v40
	v_exp_f32_e32 v38, v41
	v_exp_f32_e32 v52, v42
	v_exp_f32_e32 v56, v43
	v_add_f32_e32 v53, v134, v123
	v_add_f32_e32 v57, v136, v135
	v_add_f32_e32 v40, v38, v36
	v_add_f32_e32 v41, v39, v37
	v_add_f32_e32 v42, v56, v52
	v_add_f32_e32 v43, v57, v53
	s_nop 0
	v_add_f32_e32 v40, v42, v40
	v_add_f32_e32 v41, v43, v41
	v_add_f32_e32 v42, v44, v124
	v_add_f32_e32 v43, v45, v124
	v_add_f32_e32 v44, v60, v124
	v_add_f32_e32 v45, v61, v124
	v_exp_f32_e32 v59, v42
	v_exp_f32_e32 v61, v43
	v_exp_f32_e32 v58, v44
	v_exp_f32_e32 v60, v45
	v_add_f32_e32 v44, v62, v124
	v_add_f32_e32 v45, v63, v124
	v_pk_add_f32 v[40:41], v[40:41], v[40:41] op_sel_hi:[0,1]
	v_exp_f32_e32 v53, v44
	v_exp_f32_e32 v57, v45
	v_add_f32_e32 v42, v60, v58
	v_add_f32_e32 v43, v61, v59
	s_nop 0
	v_pk_add_f32 v[132:133], v[42:43], v[42:43] op_sel_hi:[0,1]
	v_add_f32_e32 v42, v46, v124
	v_add_f32_e32 v43, v47, v124
	v_add_f32_e32 v125, v57, v53
	v_exp_f32_e32 v37, v42
	v_exp_f32_e32 v39, v43
	v_add_f32_e32 v42, v48, v124
	v_add_f32_e32 v43, v49, v124
	v_add_f32_e32 v44, v64, v124
	v_add_f32_e32 v45, v65, v124
	v_exp_f32_e32 v40, v42
	v_exp_f32_e32 v132, v43
	v_exp_f32_e32 v62, v44
	v_exp_f32_e32 v124, v45
	v_add_f32_e32 v63, v39, v37
	v_add_f32_e32 v42, v132, v40
	v_add_f32_e32 v43, v133, v41
	v_cvt_pk_bf16_f32 v47, v126, v34
	v_add_f32_e32 v44, v124, v62
	v_add_f32_e32 v45, v125, v63
	v_cvt_pk_bf16_f32 v34, v52, v56
	v_add_f32_e32 v42, v44, v42
	v_add_f32_e32 v43, v45, v43
	v_cvt_pk_bf16_f32 v45, v40, v132
	v_cvt_pk_bf16_f32 v40, v54, v130
	v_add3_u32 v54, s6, v119, v116
	v_cvt_pk_bf16_f32 v44, v37, v39
	v_cvt_pk_bf16_f32 v37, v62, v124
	v_add_u32_e32 v62, 0x3000, v54
	v_add_f32_e32 v41, v42, v43
	v_cvt_pk_bf16_f32 v42, v36, v38
	v_cvt_pk_bf16_f32 v38, v129, v51
	v_cvt_pk_bf16_f32 v39, v128, v50
	v_cvt_pk_bf16_f32 v36, v53, v57
	ds_read2_b64 v[50:53], v62 offset0:160 offset1:162
	v_add_u32_e32 v63, 0x2000, v54
	v_cvt_pk_bf16_f32 v46, v127, v35
	v_cvt_pk_bf16_f32 v48, v55, v131
	v_cvt_pk_bf16_f32 v43, v59, v61
	v_cvt_pk_bf16_f32 v35, v58, v60
	ds_read2_b64 v[54:57], v63 offset0:128 offset1:130
	ds_read2_b64 v[58:61], v63 offset0:132 offset1:134
	v_cvt_pk_bf16_f32 v49, v123, v134
	v_add_f32_e32 v105, v105, v41
	v_cvt_pk_bf16_f32 v41, v135, v136
	ds_read2_b64 v[124:127], v62 offset0:164 offset1:166
	ds_read2_b64 v[128:131], v63 offset0:136 offset1:138
	s_waitcnt lgkmcnt(3)
	v_mfma_f32_32x32x16_bf16 v[18:33], v[54:57], v[46:49], v[18:33]
	v_mfma_f32_32x32x16_bf16 v[2:17], v[50:53], v[46:49], v[2:17]
	ds_read2_b64 v[54:57], v62 offset0:168 offset1:170
	ds_read2_b64 v[50:53], v63 offset0:140 offset1:142
	s_waitcnt lgkmcnt(4)
	v_mfma_f32_32x32x16_bf16 v[18:33], v[58:61], v[42:45], v[18:33]
	ds_read2_b64 v[58:61], v62 offset0:172 offset1:174
	s_waitcnt lgkmcnt(4)
	v_mfma_f32_32x32x16_bf16 v[2:17], v[124:127], v[42:45], v[2:17]
	s_waitcnt lgkmcnt(3)
	v_mfma_f32_32x32x16_bf16 v[18:33], v[128:131], v[38:41], v[18:33]
	s_waitcnt lgkmcnt(2)
	v_mfma_f32_32x32x16_bf16 v[2:17], v[54:57], v[38:41], v[2:17]
	s_waitcnt lgkmcnt(1)
	v_mfma_f32_32x32x16_bf16 v[18:33], v[50:53], v[34:37], v[18:33]
	s_waitcnt lgkmcnt(0)
	v_mfma_f32_32x32x16_bf16 v[2:17], v[58:61], v[34:37], v[2:17]
